# NA attention: K tile also loaded with whole-row lane mapping and re-fragmented through per-wave LDS (ds_write_b128 + ds_read_b128), cutting K global line accesses 4x
# speedup vs baseline: 1.0296x; 1.0080x over previous
; #define LAS __attribute__((address_space(3)))
; __device__ __forceinline__ void na_item(const bf16_t* __restrict__ PMIX, const bf16_t* __restrict__ GP, bf16_t* __restrict__ O, const float* __restrict__ bias, int item, int lane, LAS unsigned char* wl) {
;     const int q = lane & 31, hi = lane >> 5;
;     const bool lat = item < 8192;
;     int b, h, gi = 0, jh = 0, qrow;
;     if (lat) { b = item >> 11; h = (item >> 7) & 15; gi = (item >> 1) & 63; jh = item & 1; qrow = b * 4096 + gi * 64 + jh * 32 + q; }
;     else { const int it = item - 8192; b = it >> 7; h = (it >> 3) & 15; qrow = NLAT + b * 256 + (it & 7) * 32 + q; }
;     const int j = jh * 32 + q;
;     const int c0 = min(max(j - 8, 0), 48), r0 = min(max(gi - 4, 0), 56);
;     const bf16_t* qp = PMIX + (size_t)qrow * NMIXP + O_NAQ + h * 64 + hi * 8;
;     bf16x8 qf[4];
; #pragma unroll
;     for (int ks = 0; ks < 4; ++ks) qf[ks] = *reinterpret_cast<const bf16x8*>(qp + ks * 16);
;     f32x16 oT0 = {}, oT1 = {}; float m = -1e30f, l = 0.f;
;     const int ntiles = lat ? 24 : 8;
;     const float* bh = bias + h * (15 * 31);
;     LAS float* lbias = (LAS float*)(wl + 4608);
;     if (lat) {
; #pragma unroll
;         for (int i = 0; i < 4; ++i) { const int e = lane * 4 + i, krr = e >> 5, dc = e & 31; lbias[e] = bh[(r0 + krr - gi + 7) * 31 + min(dc, 30)] * LOG2E; }
;         asm volatile("s_waitcnt vmcnt(0) lgkmcnt(0)" ::: "memory"); __builtin_amdgcn_wave_barrier();
;     }
.Lna_norot:
	v_writelane_b32 v255, s34, 38
	s_and_b64 s[2:3], s[34:35], exec
	s_movk_i32 s1, 0x2200
	s_cselect_b32 s79, s1, 0x2000
	v_writelane_b32 v255, s35, 39
	s_cmp_ge_i32 s78, s79
	s_barrier
	s_cbranch_scc1 .LBB0_625
	s_lshl_b32 s80, s89, 3
	s_add_u32 s74, s90, 0x2087a000
	v_readlane_b32 s1, v255, 37
	s_addc_u32 s75, s1, 0
	s_add_u32 s2, s90, 0x2b27a000
	s_addc_u32 s3, s1, 0
	v_readlane_b32 s8, v254, 18
	s_add_u32 s4, s90, 0x572a6000
	v_readlane_b32 s6, v255, 20
	v_readlane_b32 s9, v254, 19
	v_readlane_b32 s10, v254, 20
	v_readlane_b32 s11, v254, 21
	v_readlane_b32 s12, v254, 22
	v_readlane_b32 s13, v254, 23
	v_readlane_b32 s16, v254, 26
	v_readlane_b32 s17, v254, 27
	s_addc_u32 s5, s1, 0
	s_mul_hi_u32 s1, s6, 0x7440
	s_mulk_i32 s6, 0x7440
	v_readlane_b32 s18, v254, 28
	v_readlane_b32 s19, v254, 29
	v_readlane_b32 s20, v254, 30
	v_readlane_b32 s21, v254, 31
	s_mov_b64 s[8:9], s[16:17]
	s_add_u32 s6, s8, s6
	s_mulk_i32 s0, 0x1600
	v_and_b32_e32 v0, 63, v176
	s_addc_u32 s82, s9, s1
	s_add_i32 s88, s0, 0
	v_bfe_u32 v1, v176, 5, 1
	v_lshlrev_b32_e32 v2, 2, v0
	v_mov_b32_e32 v3, s88
	v_bfe_u32 v167, v176, 3, 3
	s_movk_i32 s0, 0x90
	v_lshlrev_b32_e32 v168, 2, v1
	v_and_b32_e32 v128, 28, v2
	v_mad_u32_u24 v5, v167, s0, v3
	v_xor_b32_e32 v169, 0x80, v2
	v_or_b32_e32 v133, 8, v168
	v_lshlrev_b32_e32 v2, 4, v1
	v_mov_b32_e32 v3, v195
	v_or_b32_e32 v132, 32, v168
	v_lshl_add_u64 v[142:143], s[74:75], 0, v[2:3]
	v_lshlrev_b32_e32 v2, 1, v133
	v_and_b32_e32 v164, 31, v176
	v_lshl_add_u32 v166, v0, 4, s88
	v_or_b32_e32 v0, 3, v128
	v_and_b32_e32 v4, 1, v176
	v_or_b32_e32 v136, 40, v168
	v_lshl_add_u64 v[148:149], s[2:3], 0, v[2:3]
	v_lshl_add_u64 v[150:151], s[4:5], 0, v[2:3]
	v_lshlrev_b32_e32 v2, 1, v132
	v_lshlrev_b32_e32 v194, 3, v1
	v_min_u32_e32 v130, 30, v0
	v_lshlrev_b32_e32 v0, 5, v4
	v_lshlrev_b32_e32 v4, 6, v4
	v_lshl_add_u32 v6, v164, 1, s88
	v_mul_u32_u24_e32 v7, 0x240, v1
	v_mul_u32_u24_e32 v8, 0x90, v133
	v_lshl_add_u64 v[152:153], s[2:3], 0, v[2:3]
	v_lshl_add_u64 v[154:155], s[4:5], 0, v[2:3]
	v_lshlrev_b32_e32 v2, 1, v136
	v_readlane_b32 s7, v255, 21
	v_writelane_b32 v255, s6, 40
	v_bfe_u32 v165, v176, 3, 3
	v_or_b32_e32 v170, 16, v168
	v_or_b32_e32 v171, 17, v168
	v_or_b32_e32 v172, 18, v168
	v_or_b32_e32 v173, 19, v168
	v_or_b32_e32 v174, 24, v168
	v_or_b32_e32 v175, 25, v168
	v_or_b32_e32 v176, 26, v168
	v_or_b32_e32 v177, 27, v168
	v_or_b32_e32 v135, 33, v168
	v_or_b32_e32 v137, 35, v168
	v_or_b32_e32 v134, 34, v168
	v_or_b32_e32 v139, 41, v168
	v_or_b32_e32 v141, 43, v168
	v_or_b32_e32 v138, 42, v168
	v_mov_b32_e32 v129, v195
	v_mov_b32_e32 v131, v195
	v_lshl_add_u64 v[144:145], s[2:3], 0, v[194:195]
	v_lshl_add_u64 v[146:147], s[4:5], 0, v[194:195]
	v_lshl_add_u64 v[156:157], s[2:3], 0, v[2:3]
	v_lshl_add_u64 v[158:159], s[4:5], 0, v[2:3]
	v_or_b32_e32 v178, 0x48, v168
	v_add_u32_e32 v179, 0x47, v168
	v_or_b32_e32 v180, 0x42, v168
	v_or_b32_e32 v181, 0x41, v168
	v_or_b32_e32 v182, 64, v168
	v_add_u32_e32 v183, 63, v168
	v_lshlrev_b32_e32 v160, 1, v194
	v_and_b32_e32 v194, 7, v164
	v_lshlrev_b32_e32 v194, 4, v194
	v_add_u32_e32 v184, v5, v194
	s_mov_b64 s[98:99], 0x14000
	v_mul_u32_u24_e32 v185, 0x90, v164
	v_lshl_add_u32 v185, v1, 4, v185
	v_add_u32_e32 v185, s88, v185
	v_add_u32_e32 v186, v6, v8
	v_bfe_u32 v229, v164, 2, 2
	v_mul_u32_u24_e32 v229, 0x90, v229
	v_bfe_u32 v253, v164, 4, 1
	v_lshl_add_u32 v229, v253, 5, v229
	v_and_b32_e32 v253, 3, v164
	v_lshl_add_u32 v229, v253, 3, v229
	v_add_u32_e32 v229, v229, v7
	v_add_u32_e32 v229, s88, v229
	v_readlane_b32 s14, v254, 24
	v_readlane_b32 s15, v254, 25
	v_readlane_b32 s22, v254, 32
	v_readlane_b32 s23, v254, 33
	s_mov_b64 s[10:11], s[18:19]
	s_mov_b64 s[12:13], s[20:21]
	s_branch .LBB0_596

.LBB0_605:
	s_lshl_b32 s85, s6, 6
	v_add_u32_e32 v2, s8, v167
	v_mov_b64_e32 v[0:1], s[74:75]
	v_mad_i64_i32 v[2:3], s[2:3], v2, s71, v[0:1]
	s_lshl_b32 s72, s85, 1
	v_lshl_add_u64 v[2:3], v[2:3], 0, s[72:73]
	v_mov_b32_e32 v161, v195
	v_lshl_add_u64 v[2:3], v[2:3], 0, v[194:195]
	global_load_dwordx4 v[64:67], v[2:3], off offset:3712
	v_lshl_add_u64 v[68:69], v[2:3], 0, s[98:99]
	v_lshl_add_u64 v[72:73], v[68:69], 0, s[98:99]
	v_lshl_add_u64 v[76:77], v[72:73], 0, s[98:99]
	global_load_dwordx4 v[68:71], v[68:69], off offset:3712
	global_load_dwordx4 v[72:75], v[72:73], off offset:3712
	global_load_dwordx4 v[76:79], v[76:77], off offset:3712
	v_add_u32_e32 v2, s8, v167
	v_mad_i64_i32 v[0:1], s[2:3], v2, s71, v[0:1]
	v_lshl_add_u64 v[0:1], v[0:1], 0, s[72:73]
	v_lshl_add_u64 v[0:1], v[0:1], 0, v[194:195]
	s_mov_b64 s[2:3], 0x1680
	v_lshl_add_u64 v[2:3], v[0:1], 0, s[2:3]
	v_add_co_u32_e32 v0, vcc, 0x1000, v0
	s_mov_b64 s[2:3], -1
	s_nop 0
	v_addc_co_u32_e32 v1, vcc, 0, v1, vcc
	global_load_dwordx4 v[80:83], v[0:1], off offset:1664
	v_lshl_add_u64 v[92:93], v[2:3], 0, s[98:99]
	v_lshl_add_u64 v[88:89], v[92:93], 0, s[98:99]
	v_lshl_add_u64 v[84:85], v[88:89], 0, s[98:99]
	global_load_dwordx4 v[84:87], v[84:85], off
	global_load_dwordx4 v[88:91], v[88:89], off
	global_load_dwordx4 v[92:95], v[92:93], off
	s_and_b64 vcc, exec, s[0:1]
	s_cbranch_vccz .LBB0_607
	s_lshl_b32 s0, s4, 8
	s_add_i32 s1, s0, 0x4020
	s_lshl_b32 s66, s4, 12
	s_lshl_b32 s67, s5, 6
	s_mov_b64 s[2:3], 0

.LBB0_609:
	v_or_b32_e32 v0, s33, v164
	v_sub_u32_e64 v0, v0, 8 clamp
	v_min_u32_e32 v32, 48, v0
	v_add_u32_e32 v2, s1, v167
	v_mov_b64_e32 v[0:1], s[74:75]
	v_mad_i64_i32 v[2:3], s[2:3], v2, s71, v[0:1]
	v_lshl_add_u64 v[2:3], v[2:3], 0, s[72:73]
	v_mov_b32_e32 v161, v195
	v_lshl_add_u64 v[2:3], v[2:3], 0, v[194:195]
	global_load_dwordx4 v[96:99], v[2:3], off offset:3712
	v_lshl_add_u64 v[100:101], v[2:3], 0, s[98:99]
	v_lshl_add_u64 v[104:105], v[100:101], 0, s[98:99]
	v_lshl_add_u64 v[108:109], v[104:105], 0, s[98:99]
	global_load_dwordx4 v[100:103], v[100:101], off offset:3712
	global_load_dwordx4 v[104:107], v[104:105], off offset:3712
	global_load_dwordx4 v[108:111], v[108:109], off offset:3712
	v_add_u32_e32 v2, s1, v167
	v_mad_i64_i32 v[0:1], s[2:3], v2, s71, v[0:1]
	v_lshl_add_u64 v[0:1], v[0:1], 0, s[72:73]
	v_lshl_add_u64 v[0:1], v[0:1], 0, v[194:195]
	s_mov_b64 s[2:3], 0x1680
	v_lshl_add_u64 v[2:3], v[0:1], 0, s[2:3]
	v_add_co_u32_e32 v0, vcc, s96, v0
	v_cmp_lt_u32_e64 s[2:3], v168, v32
	s_nop 0
	v_addc_co_u32_e32 v1, vcc, 0, v1, vcc
	global_load_dwordx4 v[112:115], v[0:1], off offset:1664
	v_lshl_add_u64 v[124:125], v[2:3], 0, s[98:99]
	v_lshl_add_u64 v[120:121], v[124:125], 0, s[98:99]
	v_lshl_add_u64 v[116:117], v[120:121], 0, s[98:99]
	global_load_dwordx4 v[116:119], v[116:117], off
	global_load_dwordx4 v[120:123], v[120:121], off
	global_load_dwordx4 v[124:127], v[124:125], off
	v_or_b32_e32 v0, 1, v168
	v_cmp_lt_u32_e64 s[6:7], v0, v32
	v_or_b32_e32 v0, 3, v168
	v_or_b32_e32 v1, 2, v168
	v_cmp_lt_u32_e64 s[10:11], v0, v32
	v_or_b32_e32 v0, 9, v168
	v_cmp_lt_u32_e64 s[4:5], v1, v32
	v_or_b32_e32 v1, 10, v168
	v_cmp_lt_u32_e64 s[14:15], v0, v32
	v_or_b32_e32 v0, 11, v168
	v_cmp_lt_u32_e64 s[12:13], v1, v32
	v_cmp_lt_u32_e64 s[16:17], v0, v32
	v_add_u32_e32 v0, s33, v164
	v_or_b32_e32 v1, 0x4a, v168
	v_sub_u32_e32 v1, v1, v0
	v_min_u32_e32 v1, 30, v1
	v_lshlrev_b32_e32 v161, 2, v1
	v_or_b32_e32 v1, 0x49, v168
	v_sub_u32_e32 v1, v1, v0
	v_min_u32_e32 v1, 30, v1
	v_lshlrev_b32_e32 v188, 2, v1
	v_sub_u32_e32 v1, v178, v0
	v_min_u32_e32 v1, 30, v1
	v_lshlrev_b32_e32 v189, 2, v1
	v_sub_u32_e32 v1, v179, v0
	v_min_u32_e32 v1, 30, v1
	v_lshlrev_b32_e32 v190, 2, v1
	v_sub_u32_e32 v1, v180, v0
	v_min_u32_e32 v1, 30, v1
	v_lshlrev_b32_e32 v191, 2, v1
	v_sub_u32_e32 v1, v181, v0
	v_min_u32_e32 v1, 30, v1
	v_lshlrev_b32_e32 v192, 2, v1
	v_sub_u32_e32 v1, v182, v0
	v_min_u32_e32 v1, 30, v1
	v_lshlrev_b32_e32 v193, 2, v1
	v_sub_u32_e32 v1, v183, v0
	v_min_u32_e32 v1, 30, v1
	v_sub_u32_e32 v0, v168, v0
	v_lshlrev_b32_e32 v198, 2, v1
	v_max_i32_e32 v1, 0xffffffc6, v0
	v_add_u32_e32 v1, 58, v1
	v_min_u32_e32 v1, 30, v1
	v_lshlrev_b32_e32 v199, 2, v1
	v_max_i32_e32 v1, 0xffffffc7, v0
	v_add_u32_e32 v1, 57, v1
	v_min_u32_e32 v1, 30, v1
	v_lshlrev_b32_e32 v200, 2, v1
	v_max_i32_e32 v1, 0xffffffc8, v0
	v_add_u32_e32 v1, 56, v1
	v_min_u32_e32 v1, 30, v1
	v_lshlrev_b32_e32 v201, 2, v1
	v_max_i32_e32 v1, 0xffffffc9, v0
	v_add_u32_e32 v1, 55, v1
	v_min_u32_e32 v1, 30, v1
	v_lshlrev_b32_e32 v202, 2, v1
	v_max_i32_e32 v1, 0xffffffce, v0
	v_add_u32_e32 v1, 50, v1
	v_min_u32_e32 v1, 30, v1
	v_lshlrev_b32_e32 v203, 2, v1
	v_max_i32_e32 v1, 0xffffffcf, v0
	v_add_u32_e32 v1, 49, v1
	v_min_u32_e32 v1, 30, v1
	v_lshlrev_b32_e32 v204, 2, v1
	v_max_i32_e32 v1, 0xffffffd0, v0
	v_add_u32_e32 v1, 48, v1
	v_min_u32_e32 v1, 30, v1
	v_lshlrev_b32_e32 v205, 2, v1
	v_max_i32_e32 v1, 0xffffffd1, v0
	v_add_u32_e32 v1, 47, v1
	v_min_u32_e32 v1, 30, v1
	v_lshlrev_b32_e32 v206, 2, v1
	v_max_i32_e32 v1, 0xffffffd6, v0
	v_add_u32_e32 v1, 42, v1
	v_min_u32_e32 v1, 30, v1
	v_lshlrev_b32_e32 v207, 2, v1
	v_max_i32_e32 v1, 0xffffffd7, v0
	v_add_u32_e32 v1, 41, v1
	v_min_u32_e32 v1, 30, v1
	v_lshlrev_b32_e32 v208, 2, v1
	v_max_i32_e32 v1, 0xffffffd8, v0
	v_add_u32_e32 v1, 40, v1
	v_min_u32_e32 v1, 30, v1
	v_lshlrev_b32_e32 v209, 2, v1
	v_max_i32_e32 v1, 0xffffffd9, v0
	v_add_u32_e32 v1, 39, v1
	v_min_u32_e32 v1, 30, v1
	v_lshlrev_b32_e32 v210, 2, v1
	v_max_i32_e32 v1, 0xffffffde, v0
	v_add_u32_e32 v1, 34, v1
	v_add_u32_e32 v2, 16, v32
	v_cmp_ge_u32_e32 vcc, v170, v32
	v_min_u32_e32 v1, 30, v1
	s_add_i32 s86, s0, 0x4000
	s_and_b64 s[18:19], vcc, s[2:3]
	v_cmp_ge_u32_e32 vcc, v171, v32
	v_cmp_lt_u32_e64 s[0:1], v171, v2
	v_lshlrev_b32_e32 v211, 2, v1
	v_max_i32_e32 v1, 0xffffffdf, v0
	s_and_b64 s[20:21], vcc, s[0:1]
	v_cmp_ge_u32_e32 vcc, v172, v32
	v_cmp_lt_u32_e64 s[0:1], v172, v2
	v_add_u32_e32 v1, 33, v1
	s_and_b64 s[22:23], vcc, s[0:1]
	v_cmp_ge_u32_e32 vcc, v173, v32
	v_cmp_lt_u32_e64 s[0:1], v173, v2
	v_min_u32_e32 v1, 30, v1
	s_and_b64 s[24:25], vcc, s[0:1]
	v_cmp_ge_u32_e32 vcc, v174, v32
	v_cmp_lt_u32_e64 s[0:1], v174, v2
	v_lshlrev_b32_e32 v212, 2, v1
	v_max_i32_e32 v1, 0xffffffe0, v0
	s_and_b64 s[26:27], vcc, s[0:1]
	v_cmp_ge_u32_e32 vcc, v175, v32
	v_cmp_lt_u32_e64 s[0:1], v175, v2
	v_add_u32_e32 v1, 32, v1
	s_and_b64 s[28:29], vcc, s[0:1]
	v_cmp_ge_u32_e32 vcc, v176, v32
	v_cmp_lt_u32_e64 s[0:1], v176, v2
	v_min_u32_e32 v1, 30, v1
	s_and_b64 s[30:31], vcc, s[0:1]
	v_cmp_ge_u32_e32 vcc, v177, v32
	v_cmp_lt_u32_e64 s[0:1], v177, v2
	v_lshlrev_b32_e32 v213, 2, v1
	v_max_i32_e32 v1, 0xffffffe1, v0
	s_and_b64 s[34:35], vcc, s[0:1]
	v_cmp_ge_u32_e32 vcc, v132, v32
	v_cmp_lt_u32_e64 s[0:1], v170, v32
	v_add_u32_e32 v1, 31, v1
	s_and_b64 s[36:37], vcc, s[0:1]
	v_cmp_ge_u32_e32 vcc, v135, v32
	v_cmp_lt_u32_e64 s[0:1], v171, v32
	v_min_u32_e32 v1, 30, v1
	s_and_b64 s[38:39], vcc, s[0:1]
	v_cmp_ge_u32_e32 vcc, v134, v32
	v_cmp_lt_u32_e64 s[0:1], v172, v32
	v_lshlrev_b32_e32 v214, 2, v1
	v_max_i32_e32 v1, 0xffffffe6, v0
	s_and_b64 s[40:41], vcc, s[0:1]
	v_cmp_ge_u32_e32 vcc, v137, v32
	v_cmp_lt_u32_e64 s[0:1], v173, v32
	v_lshlrev_b32_e32 v215, 2, v1
	v_max_i32_e32 v1, 0xffffffe7, v0
	s_and_b64 s[42:43], vcc, s[0:1]
	v_cmp_ge_u32_e32 vcc, v136, v32
	v_cmp_lt_u32_e64 s[0:1], v174, v32
	v_lshlrev_b32_e32 v216, 2, v1
	v_max_i32_e32 v1, 0xffffffe8, v0
	s_and_b64 s[54:55], vcc, s[0:1]
	v_cmp_ge_u32_e32 vcc, v139, v32
	v_cmp_lt_u32_e64 s[0:1], v175, v32
	v_lshlrev_b32_e32 v217, 2, v1
	v_max_i32_e32 v1, 0xffffffe9, v0
	s_and_b64 s[56:57], vcc, s[0:1]
	v_cmp_ge_u32_e32 vcc, v138, v32
	v_cmp_lt_u32_e64 s[0:1], v176, v32
	v_lshlrev_b32_e32 v218, 2, v1
	v_max_i32_e32 v1, 0xffffffee, v0
	s_and_b64 s[58:59], vcc, s[0:1]
	v_cmp_ge_u32_e32 vcc, v141, v32
	v_cmp_lt_u32_e64 s[0:1], v177, v32
	v_lshlrev_b32_e32 v219, 2, v1
	v_max_i32_e32 v1, 0xffffffef, v0
	s_and_b64 s[60:61], vcc, s[0:1]
	v_lshlrev_b32_e32 v220, 2, v1
	v_max_i32_e32 v1, -16, v0
	v_max_i32_e32 v0, -15, v0
	s_add_i32 s0, s66, s67
	v_mov_b32_e32 v232, 0
	v_cmp_lt_u32_e64 s[8:9], v133, v32
	v_cmp_lt_u32_e64 s[44:45], v135, v32
	v_cmp_lt_u32_e64 s[46:47], v132, v32
	v_cmp_lt_u32_e64 s[48:49], v137, v32
	v_cmp_lt_u32_e64 s[50:51], v134, v32
	v_cmp_lt_u32_e64 s[52:53], v139, v32
	v_cmp_lt_u32_e64 s[62:63], v136, v32
	v_cmp_lt_u32_e64 s[64:65], v141, v32
	v_lshl_add_u64 v[162:163], s[74:75], 0, v[194:195]
	v_lshl_add_u64 v[162:163], v[162:163], 0, s[72:73]
	v_lshlrev_b32_e32 v221, 2, v1
	v_lshlrev_b32_e32 v231, 2, v0
	s_add_i32 s87, s0, 0x60
	v_mov_b32_e32 v140, 0xf149f2ca
	s_mov_b32 s93, -14
	v_mov_b32_e32 v16, 0
	v_mov_b32_e32 v17, v232
	v_mov_b32_e32 v18, v232
	v_mov_b32_e32 v19, v232
	v_mov_b32_e32 v20, v232
	v_mov_b32_e32 v21, v232
	v_mov_b32_e32 v22, v232
	v_mov_b32_e32 v23, v232
	v_mov_b32_e32 v24, v232
	v_mov_b32_e32 v25, v232
	v_mov_b32_e32 v26, v232
	v_mov_b32_e32 v27, v232
	v_mov_b32_e32 v28, v232
	v_mov_b32_e32 v29, v232
	v_mov_b32_e32 v30, v232
	v_mov_b32_e32 v31, v232
	v_mov_b32_e32 v0, 0
	v_mov_b32_e32 v1, v232
	v_mov_b32_e32 v2, v232
	v_mov_b32_e32 v3, v232
	v_mov_b32_e32 v4, v232
	v_mov_b32_e32 v5, v232
	v_mov_b32_e32 v6, v232
	v_mov_b32_e32 v7, v232
	v_mov_b32_e32 v8, v232
	v_mov_b32_e32 v9, v232
	v_mov_b32_e32 v10, v232
	v_mov_b32_e32 v11, v232
	v_mov_b32_e32 v12, v232
	v_mov_b32_e32 v13, v232
	v_mov_b32_e32 v14, v232
	v_mov_b32_e32 v15, v232
	s_mov_b32 s83, s88
	v_cmp_lt_u32_e64 s[66:67], v138, v32
	s_branch .LBB0_611

.LBB0_611:
	s_waitcnt vmcnt(12)
	ds_write_b128 v184, v[64:67] offset:46080
	ds_write_b128 v184, v[68:71] offset:47232
	ds_write_b128 v184, v[72:75] offset:48384
	ds_write_b128 v184, v[76:79] offset:49536
	s_add_i32 s81, s93, 14
	s_add_i32 s33, s93, 16
	s_cmp_ge_u32 s33, s84
	s_waitcnt vmcnt(11)
	ds_write_b128 v184, v[80:83]
	s_waitcnt vmcnt(8)
	ds_write_b128 v184, v[92:95] offset:1152
	ds_write_b128 v184, v[88:91] offset:2304
	ds_write_b128 v184, v[84:87] offset:3456
	s_waitcnt lgkmcnt(4)
	ds_read_b128 v[64:67], v185 offset:46080
	ds_read_b128 v[68:71], v185 offset:46112
	ds_read_b128 v[72:75], v185 offset:46144
	ds_read_b128 v[76:79], v185 offset:46176
	s_waitcnt lgkmcnt(0)
	v_mfma_f32_32x32x16_bf16 v[32:47], v[64:67], v[48:51], 0
	v_mfma_f32_32x32x16_bf16 v[32:47], v[68:71], v[52:55], v[32:47]
	v_mfma_f32_32x32x16_bf16 v[32:47], v[72:75], v[56:59], v[32:47]
	v_mfma_f32_32x32x16_bf16 v[32:47], v[76:79], v[60:63], v[32:47]
	s_cbranch_scc1 .LBB0_617
	s_cmp_lt_u32 s81, 14
	s_cselect_b64 s[0:1], -1, 0
	s_and_b64 s[0:1], s[76:77], s[0:1]
	s_andn2_b64 vcc, exec, s[0:1]
	s_mov_b64 s[0:1], -1
	s_cbranch_vccz .LBB0_614
	s_and_b64 s[0:1], s[76:77], exec
	s_cselect_b32 s0, s93, s33
	s_lshl_b32 s0, s0, 5
	s_add_i32 s68, s0, s86
	s_mov_b64 s[0:1], 0

.LBB0_616:
	v_add_u32_e32 v82, s68, v167
	v_mov_b64_e32 v[80:81], s[74:75]
	v_add_u32_e32 v64, s68, v167
	v_mad_i64_i32 v[80:81], s[0:1], v82, s71, v[80:81]
	v_mad_i64_i32 v[76:77], s[0:1], v64, s71, v[162:163]
	v_lshl_add_u64 v[80:81], v[80:81], 0, s[72:73]
	v_lshl_add_u64 v[80:81], v[80:81], 0, v[194:195]
	s_mov_b64 s[0:1], 0x1680
	v_lshl_add_u64 v[92:93], v[80:81], 0, s[0:1]
	v_add_co_u32_e32 v80, vcc, s96, v80
	global_load_dwordx4 v[64:67], v[76:77], off offset:3712
	v_lshl_add_u64 v[68:69], v[76:77], 0, s[98:99]
	v_lshl_add_u64 v[72:73], v[68:69], 0, s[98:99]
	v_lshl_add_u64 v[76:77], v[72:73], 0, s[98:99]
	global_load_dwordx4 v[68:71], v[68:69], off offset:3712
	global_load_dwordx4 v[72:75], v[72:73], off offset:3712
	global_load_dwordx4 v[76:79], v[76:77], off offset:3712
	v_addc_co_u32_e32 v81, vcc, 0, v81, vcc
	global_load_dwordx4 v[80:83], v[80:81], off offset:1664
	s_nop 0
	v_lshl_add_u64 v[92:93], v[92:93], 0, s[98:99]
	v_lshl_add_u64 v[88:89], v[92:93], 0, s[98:99]
	v_lshl_add_u64 v[84:85], v[88:89], 0, s[98:99]
	global_load_dwordx4 v[84:87], v[84:85], off
	global_load_dwordx4 v[88:91], v[88:89], off
	global_load_dwordx4 v[92:95], v[92:93], off

.LBB0_619:
	s_nop 3
	v_max_f32_e32 v222, v33, v33
	v_max_f32_e32 v223, v32, v32
	v_max_f32_e32 v222, v223, v222
	v_max3_f32 v222, v222, v34, v35
	v_max3_f32 v222, v222, v36, v37
	v_max3_f32 v222, v222, v38, v39
	v_max3_f32 v222, v222, v40, v41
	v_max3_f32 v222, v222, v42, v43
	v_max3_f32 v222, v222, v44, v45
	v_max3_f32 v222, v222, v46, v47
	ds_bpermute_b32 v223, v169, v222
	s_waitcnt lgkmcnt(0)
	s_add_i32 s0, s93, 17
	s_cmp_ge_u32 s0, s84
	s_waitcnt lgkmcnt(0)
	v_max3_f32 v233, v140, v222, v223
	v_sub_f32_e32 v32, v32, v233
	v_exp_f32_e32 v234, v32
	v_sub_f32_e32 v32, v33, v233
	v_exp_f32_e32 v235, v32
	v_sub_f32_e32 v32, v34, v233
	v_exp_f32_e32 v236, v32
	v_sub_f32_e32 v32, v35, v233
	v_exp_f32_e32 v237, v32
	v_sub_f32_e32 v32, v36, v233
	v_exp_f32_e32 v238, v32
	v_sub_f32_e32 v32, v37, v233
	v_exp_f32_e32 v239, v32
	v_sub_f32_e32 v32, v38, v233
	v_exp_f32_e32 v240, v32
	v_sub_f32_e32 v32, v39, v233
	v_exp_f32_e32 v241, v32
	v_sub_f32_e32 v32, v40, v233
	v_exp_f32_e32 v242, v32
	v_sub_f32_e32 v32, v41, v233
	v_exp_f32_e32 v243, v32
	v_sub_f32_e32 v32, v42, v233
	v_exp_f32_e32 v244, v32
	v_sub_f32_e32 v32, v43, v233
	ds_read_b64_tr_b16 v[36:37], v229
	ds_read_b64_tr_b16 v[38:39], v229 offset:1152
	v_sub_f32_e32 v140, v140, v233
	v_exp_f32_e32 v245, v32
	v_sub_f32_e32 v32, v44, v233
	v_exp_f32_e32 v140, v140
	s_waitcnt lgkmcnt(2)
	s_waitcnt lgkmcnt(0)
	v_exp_f32_e32 v246, v32
	v_sub_f32_e32 v32, v45, v233
	v_exp_f32_e32 v247, v32
	v_sub_f32_e32 v32, v46, v233
	v_exp_f32_e32 v248, v32
	v_sub_f32_e32 v32, v47, v233
	v_exp_f32_e32 v249, v32
	v_cvt_pk_bf16_f32 v32, v234, v235
	v_cvt_pk_bf16_f32 v33, v236, v237
	v_cvt_pk_bf16_f32 v34, v238, v239
	v_cvt_pk_bf16_f32 v35, v240, v241
	v_pk_mul_f32 v[30:31], v[30:31], v[140:141] op_sel_hi:[1,0]
	v_pk_mul_f32 v[28:29], v[28:29], v[140:141] op_sel_hi:[1,0]
	v_pk_mul_f32 v[26:27], v[26:27], v[140:141] op_sel_hi:[1,0]
	v_pk_mul_f32 v[24:25], v[24:25], v[140:141] op_sel_hi:[1,0]
	v_pk_mul_f32 v[22:23], v[22:23], v[140:141] op_sel_hi:[1,0]
	v_pk_mul_f32 v[20:21], v[20:21], v[140:141] op_sel_hi:[1,0]
	v_pk_mul_f32 v[18:19], v[18:19], v[140:141] op_sel_hi:[1,0]
	v_pk_mul_f32 v[16:17], v[16:17], v[140:141] op_sel_hi:[1,0]
	v_pk_mul_f32 v[14:15], v[14:15], v[140:141] op_sel_hi:[1,0]
	v_pk_mul_f32 v[12:13], v[12:13], v[140:141] op_sel_hi:[1,0]
	v_mfma_f32_32x32x16_bf16 v[16:31], v[36:39], v[32:35], v[16:31]
	ds_read_b64_tr_b16 v[36:37], v229 offset:64
	ds_read_b64_tr_b16 v[38:39], v229 offset:1216
	s_waitcnt lgkmcnt(2)
	v_pk_mul_f32 v[10:11], v[10:11], v[140:141] op_sel_hi:[1,0]
	s_waitcnt lgkmcnt(0)
	v_pk_mul_f32 v[8:9], v[8:9], v[140:141] op_sel_hi:[1,0]
	v_pk_mul_f32 v[6:7], v[6:7], v[140:141] op_sel_hi:[1,0]
	v_pk_mul_f32 v[4:5], v[4:5], v[140:141] op_sel_hi:[1,0]
	v_pk_mul_f32 v[2:3], v[2:3], v[140:141] op_sel_hi:[1,0]
	v_pk_mul_f32 v[0:1], v[0:1], v[140:141] op_sel_hi:[1,0]
	s_nop 1
	v_mfma_f32_32x32x16_bf16 v[0:15], v[36:39], v[32:35], v[0:15]
	ds_read_b64_tr_b16 v[36:37], v229 offset:2304
	ds_read_b64_tr_b16 v[38:39], v229 offset:3456
	s_waitcnt lgkmcnt(2)
	v_cvt_pk_bf16_f32 v32, v242, v243
	s_waitcnt lgkmcnt(0)
	v_cvt_pk_bf16_f32 v33, v244, v245
	v_cvt_pk_bf16_f32 v34, v246, v247
	v_cvt_pk_bf16_f32 v35, v248, v249
	s_nop 1
	v_mfma_f32_32x32x16_bf16 v[16:31], v[36:39], v[32:35], v[16:31]
	ds_read_b64_tr_b16 v[36:37], v229 offset:2368
	ds_read_b64_tr_b16 v[38:39], v229 offset:3520
	s_waitcnt lgkmcnt(2)
	s_waitcnt lgkmcnt(0)
	s_waitcnt vmcnt(3)
	ds_write_b128 v184, v[96:99] offset:46080
	ds_write_b128 v184, v[100:103] offset:47232
	ds_write_b128 v184, v[104:107] offset:48384
	ds_write_b128 v184, v[108:111] offset:49536
	ds_write_b128 v184, v[112:115]
	s_waitcnt vmcnt(0)
	ds_write_b128 v184, v[124:127] offset:1152
	ds_write_b128 v184, v[120:123] offset:2304
	ds_write_b128 v184, v[116:119] offset:3456
	v_mfma_f32_32x32x16_bf16 v[0:15], v[36:39], v[32:35], v[0:15]
	s_waitcnt lgkmcnt(4)
	ds_read_b128 v[96:99], v185 offset:46080
	ds_read_b128 v[100:103], v185 offset:46112
	ds_read_b128 v[104:107], v185 offset:46144
	ds_read_b128 v[108:111], v185 offset:46176
	s_waitcnt lgkmcnt(0)
	v_mfma_f32_32x32x16_bf16 v[32:47], v[96:99], v[48:51], 0
	v_mfma_f32_32x32x16_bf16 v[32:47], v[100:103], v[52:55], v[32:47]
	v_mfma_f32_32x32x16_bf16 v[32:47], v[104:107], v[56:59], v[32:47]
	v_mfma_f32_32x32x16_bf16 v[32:47], v[108:111], v[60:63], v[32:47]
	s_cbranch_scc1 .LBB0_623
	s_cmp_lt_u32 s81, 13
	s_cselect_b64 vcc, -1, 0
	s_and_b64 vcc, s[76:77], vcc
	s_and_b64 vcc, exec, vcc
	s_mov_b32 s1, s87
	s_cbranch_vccnz .LBB0_622
	s_add_i32 s1, s93, 1
	s_and_b64 vcc, s[76:77], exec
	s_cselect_b32 s0, s1, s0
	s_lshl_b32 s0, s0, 5
	s_add_i32 s1, s0, s86
.LBB0_622:
	v_add_u32_e32 v114, s1, v167
	v_mov_b64_e32 v[112:113], s[74:75]
	v_add_u32_e32 v96, s1, v167
	v_mad_i64_i32 v[112:113], s[0:1], v114, s71, v[112:113]
	v_lshl_add_u64 v[112:113], v[112:113], 0, s[72:73]
	v_mad_i64_i32 v[108:109], vcc, v96, s71, v[162:163]
	v_lshl_add_u64 v[112:113], v[112:113], 0, v[194:195]
	s_mov_b64 s[0:1], 0x1680
	v_lshl_add_u64 v[124:125], v[112:113], 0, s[0:1]
	v_add_co_u32_e32 v112, vcc, s96, v112
	global_load_dwordx4 v[96:99], v[108:109], off offset:3712
	v_lshl_add_u64 v[100:101], v[108:109], 0, s[98:99]
	v_lshl_add_u64 v[104:105], v[100:101], 0, s[98:99]
	v_lshl_add_u64 v[108:109], v[104:105], 0, s[98:99]
	global_load_dwordx4 v[100:103], v[100:101], off offset:3712
	global_load_dwordx4 v[104:107], v[104:105], off offset:3712
	global_load_dwordx4 v[108:111], v[108:109], off offset:3712
	v_addc_co_u32_e32 v113, vcc, 0, v113, vcc
	global_load_dwordx4 v[112:115], v[112:113], off offset:1664
	s_nop 0
	v_lshl_add_u64 v[124:125], v[124:125], 0, s[98:99]
	v_lshl_add_u64 v[120:121], v[124:125], 0, s[98:99]
	v_lshl_add_u64 v[116:117], v[120:121], 0, s[98:99]
	global_load_dwordx4 v[116:119], v[116:117], off
	global_load_dwordx4 v[120:123], v[120:121], off
	global_load_dwordx4 v[124:127], v[124:125], off
